# v24 with the mid-segment setprio flip moved from after MFMA 16 to after MFMA 24
# baseline (speedup 1.0000x reference)
; #define PG8_STAGE(bufoff, gbase, voff) do { _Pragma("unroll") for (int _i = 0; _i < 2; ++_i) \
;         __builtin_amdgcn_global_load_lds((const unsigned*)((const char*)(gbase) + (voff)[_i]), (PG8_LAS unsigned*)(lds + (bufoff) + ldsw + _i * 8192), 16, 0, 0); } while (0)
; #define PG8_LDA(dst, b, h) do { _Pragma("unroll") for (int m = 0; m < 4; ++m) _Pragma("unroll") for (int k = 0; k < 2; ++k) dst[m][k] = *(const PG8_LAS bf16x8*)(lds + PG8_SA(b, h) + aoff + m * 2048 + k * 1024); } while (0)
; #define PG8_LDB(dst, b, h) do { _Pragma("unroll") for (int n = 0; n < 2; ++n) _Pragma("unroll") for (int k = 0; k < 2; ++k) dst[n][k] = *(const PG8_LAS bf16x8*)(lds + PG8_SB(b, h) + boff + n * 2048 + k * 1024); } while (0)
; #define PG8_MMA(ai, bj, At, Bt) do { __builtin_amdgcn_s_setprio(1); _Pragma("unroll") for (int m = 0; m < 4; ++m) _Pragma("unroll") for (int n = 0; n < 2; ++n) _Pragma("unroll") for (int k = 0; k < 2; ++k) \
;         acc[ai][bj][m][n] = __builtin_amdgcn_mfma_f32_16x16x32_bf16(Bt[n][k], At[m][k], acc[ai][bj][m][n], 0, 0, 0); __builtin_amdgcn_s_setprio(0); } while (0)
; #define PG8_WAIT_V(n) asm volatile("s_waitcnt vmcnt(" #n ")" ::: "memory")
; #define PG8_WAIT_L(n) asm volatile("s_waitcnt lgkmcnt(" #n ")" ::: "memory")
; template <class Epi, class Sched, bool ALIGN_EPI = false, bool SP2 = false>
; __device__ __forceinline__ void gemm_phase(PG8_LAS unsigned char* lds, const Gemm g, const Sched& S, const Epi& E) {
;     ...
;             const bool last = (t == nt - 2);
;             const char* a1 = cA + (size_t)(t + 1) * kstep;
;             const char* a2 = last ? nA : cA + (size_t)(t + 2) * kstep; const char* b2 = last ? nB : cB + (size_t)(t + 2) * kstep;
;             const char* a3 = a2 + kstep; const char* b3 = b2 + kstep;
;             if (last && has_next) S.a_ready(nxt);
;             if constexpr (SP2) {
;             PG8_LDB(B0, 0, 0); PG8_LDB(B1, 0, 1); PG8_SCHED; PG8_LDA(At, 0, 0); PG8_STAGE(PG8_SA(1, 1), a1 + hstep, voffA);
;             PG8_WAIT_V(8); PG8_WAIT_L(0); PG8_BAR; PG8_MMA(0, 0, At, B0); PG8_MMA(0, 1, At, B1); PG8_BAR; PG8_SCHED;
;             PG8_LDA(At, 0, 1); PG8_STAGE(PG8_SB(0, 0), b2, voffB); PG8_STAGE(PG8_SB(0, 1), b2 + hstep, voffB); PG8_STAGE(PG8_SA(0, 0), a2, voffA);
;             PG8_WAIT_V(8); PG8_WAIT_L(0); PG8_BAR; PG8_MMA(1, 0, At, B0); PG8_MMA(1, 1, At, B1); PG8_BAR; PG8_SCHED;
.LBB0_33:
	s_add_i32 s1, s0, 2
	s_add_u32 s2, s10, 0x80
	s_addc_u32 s3, s11, 0
	s_add_i32 s33, 0, 0x10000
	s_cmp_eq_u32 s94, s0
	s_cselect_b32 s39, s35, s3
	s_cselect_b32 s38, s34, s2
	v_add_u32_e32 v80, s33, v225
	s_cselect_b32 s3, s37, vcc_hi
	s_cselect_b32 s2, s36, vcc_lo
	s_add_i32 s0, 0, 0x14000
	ds_read_b128 v[130:133], v80
	ds_read_b128 v[134:137], v80 offset:1024
	ds_read_b128 v[154:157], v80 offset:2048
	ds_read_b128 v[158:161], v80 offset:3072
	v_add_u32_e32 v80, s0, v225
	ds_read_b128 v[162:165], v80
	ds_read_b128 v[166:169], v80 offset:1024
	ds_read_b128 v[170:173], v80 offset:2048
	ds_read_b128 v[180:183], v80 offset:3072
	v_lshl_add_u64 v[174:175], s[10:11], 0, v[152:153]
	s_add_i32 m0, s84, 0xc000
	ds_read_b128 v[184:187], v227
	ds_read_b128 v[188:191], v227 offset:1024
	ds_read_b128 v[192:195], v227 offset:2048
	ds_read_b128 v[196:199], v227 offset:3072
	ds_read_b128 v[200:203], v227 offset:4096
	ds_read_b128 v[204:207], v227 offset:5120
	ds_read_b128 v[228:231], v227 offset:6144
	ds_read_b128 v[232:235], v227 offset:7168
	global_load_lds_dwordx4 v[174:175], off
	v_lshl_add_u64 v[174:175], s[10:11], 0, v[150:151]
	s_add_i32 m0, s84, 0xe000
	s_nop 0
	global_load_lds_dwordx4 v[174:175], off
	s_waitcnt vmcnt(8)
	s_waitcnt lgkmcnt(0)
	s_barrier
	s_setprio 1
	v_mfma_f32_16x16x32_bf16 v[126:129], v[130:133], v[184:187], v[126:129]
	v_mfma_f32_16x16x32_bf16 v[118:121], v[154:157], v[184:187], v[118:121]
	v_mfma_f32_16x16x32_bf16 v[110:113], v[130:133], v[192:195], v[110:113]
	v_mfma_f32_16x16x32_bf16 v[102:105], v[154:157], v[192:195], v[102:105]
	v_mfma_f32_16x16x32_bf16 v[94:97], v[130:133], v[200:203], v[94:97]
	v_mfma_f32_16x16x32_bf16 v[86:89], v[154:157], v[200:203], v[86:89]
	v_mfma_f32_16x16x32_bf16 v[76:79], v[130:133], v[228:231], v[76:79]
	v_mfma_f32_16x16x32_bf16 v[68:71], v[154:157], v[228:231], v[68:71]
	v_mfma_f32_16x16x32_bf16 v[126:129], v[134:137], v[188:191], v[126:129]
	v_mfma_f32_16x16x32_bf16 v[118:121], v[158:161], v[188:191], v[118:121]
	v_mfma_f32_16x16x32_bf16 v[110:113], v[134:137], v[196:199], v[110:113]
	v_mfma_f32_16x16x32_bf16 v[102:105], v[158:161], v[196:199], v[102:105]
	v_mfma_f32_16x16x32_bf16 v[94:97], v[134:137], v[204:207], v[94:97]
	v_mfma_f32_16x16x32_bf16 v[86:89], v[158:161], v[204:207], v[86:89]
	v_mfma_f32_16x16x32_bf16 v[76:79], v[134:137], v[232:235], v[76:79]
	v_mfma_f32_16x16x32_bf16 v[68:71], v[158:161], v[232:235], v[68:71]
	v_mfma_f32_16x16x32_bf16 v[122:125], v[162:165], v[184:187], v[122:125]
	v_mfma_f32_16x16x32_bf16 v[114:117], v[170:173], v[184:187], v[114:117]
	v_mfma_f32_16x16x32_bf16 v[106:109], v[162:165], v[192:195], v[106:109]
	v_mfma_f32_16x16x32_bf16 v[98:101], v[170:173], v[192:195], v[98:101]
	v_mfma_f32_16x16x32_bf16 v[90:93], v[162:165], v[200:203], v[90:93]
	v_mfma_f32_16x16x32_bf16 v[82:85], v[170:173], v[200:203], v[82:85]
	v_mfma_f32_16x16x32_bf16 v[72:75], v[162:165], v[228:231], v[72:75]
	v_mfma_f32_16x16x32_bf16 v[64:67], v[170:173], v[228:231], v[64:67]
	s_setprio 0
	s_setprio 1
	v_mfma_f32_16x16x32_bf16 v[122:125], v[166:169], v[188:191], v[122:125]
	v_mfma_f32_16x16x32_bf16 v[114:117], v[180:183], v[188:191], v[114:117]
	v_mfma_f32_16x16x32_bf16 v[106:109], v[166:169], v[196:199], v[106:109]
	v_mfma_f32_16x16x32_bf16 v[98:101], v[180:183], v[196:199], v[98:101]
	v_mfma_f32_16x16x32_bf16 v[90:93], v[166:169], v[204:207], v[90:93]
	v_mfma_f32_16x16x32_bf16 v[82:85], v[180:183], v[204:207], v[82:85]
	v_mfma_f32_16x16x32_bf16 v[72:75], v[166:169], v[232:235], v[72:75]
	v_mfma_f32_16x16x32_bf16 v[64:67], v[180:183], v[232:235], v[64:67]
	s_setprio 0
	s_barrier
	s_add_i32 s33, s33, s83
	v_lshl_add_u64 v[174:175], s[2:3], 0, v[140:141]
	s_mov_b32 m0, s33
	ds_read_b128 v[184:187], v227 offset:16384
	ds_read_b128 v[188:191], v227 offset:17408
	ds_read_b128 v[192:195], v227 offset:18432
	ds_read_b128 v[196:199], v227 offset:19456
	ds_read_b128 v[200:203], v227 offset:20480
	ds_read_b128 v[204:207], v227 offset:21504
	ds_read_b128 v[228:231], v227 offset:22528
	ds_read_b128 v[232:235], v227 offset:23552
	global_load_lds_dwordx4 v[174:175], off
	s_add_i32 m0, s33, 0x2000
	v_lshl_add_u64 v[208:209], s[2:3], 0, v[144:145]
	s_add_u32 s2, s2, s22
	s_addc_u32 s3, s3, 0
	s_add_i32 s0, s0, s83
	global_load_lds_dwordx4 v[208:209], off
	v_lshl_add_u64 v[236:237], s[2:3], 0, v[140:141]
	s_mov_b32 m0, s0
	v_lshl_add_u64 v[238:239], s[2:3], 0, v[144:145]
	global_load_lds_dwordx4 v[236:237], off
	s_add_i32 m0, s0, 0x2000
	v_lshl_add_u64 v[240:241], s[38:39], 0, v[138:139]
	global_load_lds_dwordx4 v[238:239], off
	s_mov_b32 m0, s84
	v_lshl_add_u64 v[242:243], s[38:39], 0, v[142:143]
	global_load_lds_dwordx4 v[240:241], off
	s_mov_b32 m0, s85
	s_nop 0
	global_load_lds_dwordx4 v[242:243], off
	s_waitcnt vmcnt(8)
	s_waitcnt lgkmcnt(0)
	s_barrier
; #define PG8_STAGE(bufoff, gbase, voff) do { _Pragma("unroll") for (int _i = 0; _i < 2; ++_i) \
;         __builtin_amdgcn_global_load_lds((const unsigned*)((const char*)(gbase) + (voff)[_i]), (PG8_LAS unsigned*)(lds + (bufoff) + ldsw + _i * 8192), 16, 0, 0); } while (0)
; #define PG8_LDA(dst, b, h) do { _Pragma("unroll") for (int m = 0; m < 4; ++m) _Pragma("unroll") for (int k = 0; k < 2; ++k) dst[m][k] = *(const PG8_LAS bf16x8*)(lds + PG8_SA(b, h) + aoff + m * 2048 + k * 1024); } while (0)
; #define PG8_LDB(dst, b, h) do { _Pragma("unroll") for (int n = 0; n < 2; ++n) _Pragma("unroll") for (int k = 0; k < 2; ++k) dst[n][k] = *(const PG8_LAS bf16x8*)(lds + PG8_SB(b, h) + boff + n * 2048 + k * 1024); } while (0)
; #define PG8_MMA(ai, bj, At, Bt) do { __builtin_amdgcn_s_setprio(1); _Pragma("unroll") for (int m = 0; m < 4; ++m) _Pragma("unroll") for (int n = 0; n < 2; ++n) _Pragma("unroll") for (int k = 0; k < 2; ++k) \
;         acc[ai][bj][m][n] = __builtin_amdgcn_mfma_f32_16x16x32_bf16(Bt[n][k], At[m][k], acc[ai][bj][m][n], 0, 0, 0); __builtin_amdgcn_s_setprio(0); } while (0)
; #define PG8_WAIT_V(n) asm volatile("s_waitcnt vmcnt(" #n ")" ::: "memory")
; #define PG8_WAIT_L(n) asm volatile("s_waitcnt lgkmcnt(" #n ")" ::: "memory")
; #define PG8_BAR __builtin_amdgcn_s_barrier()
; #define PG8_SCHED __builtin_amdgcn_sched_barrier(0)
; template <class Epi, class Sched, bool ALIGN_EPI = false, bool SP2 = false>
; __device__ __forceinline__ void gemm_phase(PG8_LAS unsigned char* lds, const Gemm g, const Sched& S, const Epi& E) {
;     ...
;             PG8_WAIT_V(8); PG8_WAIT_L(0); PG8_BAR; PG8_MMA(1, 0, At, B0); PG8_MMA(1, 1, At, B1); PG8_BAR; PG8_SCHED;
;             PG8_LDB(B0, 1, 0); PG8_LDB(B1, 1, 1); PG8_SCHED; PG8_LDA(At, 1, 0); PG8_STAGE(PG8_SA(0, 1), a2 + hstep, voffA);
;             PG8_WAIT_V(8); PG8_WAIT_L(0); PG8_BAR; PG8_MMA(0, 0, At, B0); PG8_MMA(0, 1, At, B1); PG8_BAR; PG8_SCHED;
;             PG8_LDA(At, 1, 1); PG8_STAGE(PG8_SB(1, 0), b3, voffB); PG8_STAGE(PG8_SB(1, 1), b3 + hstep, voffB); PG8_STAGE(PG8_SA(1, 0), a3, voffA);
	s_setprio 1
	v_mfma_f32_16x16x32_bf16 v[60:63], v[130:133], v[184:187], v[60:63]
	v_mfma_f32_16x16x32_bf16 v[52:55], v[154:157], v[184:187], v[52:55]
	v_mfma_f32_16x16x32_bf16 v[44:47], v[130:133], v[192:195], v[44:47]
	v_mfma_f32_16x16x32_bf16 v[36:39], v[154:157], v[192:195], v[36:39]
	v_mfma_f32_16x16x32_bf16 v[28:31], v[130:133], v[200:203], v[28:31]
	v_mfma_f32_16x16x32_bf16 v[20:23], v[154:157], v[200:203], v[20:23]
	v_mfma_f32_16x16x32_bf16 v[12:15], v[130:133], v[228:231], v[12:15]
	v_mfma_f32_16x16x32_bf16 v[4:7], v[154:157], v[228:231], v[4:7]
	v_mfma_f32_16x16x32_bf16 v[60:63], v[134:137], v[188:191], v[60:63]
	v_mfma_f32_16x16x32_bf16 v[52:55], v[158:161], v[188:191], v[52:55]
	v_mfma_f32_16x16x32_bf16 v[44:47], v[134:137], v[196:199], v[44:47]
	v_mfma_f32_16x16x32_bf16 v[36:39], v[158:161], v[196:199], v[36:39]
	v_mfma_f32_16x16x32_bf16 v[28:31], v[134:137], v[204:207], v[28:31]
	v_mfma_f32_16x16x32_bf16 v[20:23], v[158:161], v[204:207], v[20:23]
	v_mfma_f32_16x16x32_bf16 v[12:15], v[134:137], v[232:235], v[12:15]
	v_mfma_f32_16x16x32_bf16 v[4:7], v[158:161], v[232:235], v[4:7]
	v_mfma_f32_16x16x32_bf16 v[56:59], v[162:165], v[184:187], v[56:59]
	v_mfma_f32_16x16x32_bf16 v[48:51], v[170:173], v[184:187], v[48:51]
	v_mfma_f32_16x16x32_bf16 v[40:43], v[162:165], v[192:195], v[40:43]
	v_mfma_f32_16x16x32_bf16 v[32:35], v[170:173], v[192:195], v[32:35]
	v_mfma_f32_16x16x32_bf16 v[24:27], v[162:165], v[200:203], v[24:27]
	v_mfma_f32_16x16x32_bf16 v[16:19], v[170:173], v[200:203], v[16:19]
	v_mfma_f32_16x16x32_bf16 v[8:11], v[162:165], v[228:231], v[8:11]
	v_mfma_f32_16x16x32_bf16 v[0:3], v[170:173], v[228:231], v[0:3]
	s_setprio 0
	s_setprio 1
	v_mfma_f32_16x16x32_bf16 v[56:59], v[166:169], v[188:191], v[56:59]
	v_mfma_f32_16x16x32_bf16 v[48:51], v[180:183], v[188:191], v[48:51]
	v_mfma_f32_16x16x32_bf16 v[40:43], v[166:169], v[196:199], v[40:43]
	v_mfma_f32_16x16x32_bf16 v[32:35], v[180:183], v[196:199], v[32:35]
	v_mfma_f32_16x16x32_bf16 v[24:27], v[166:169], v[204:207], v[24:27]
	v_mfma_f32_16x16x32_bf16 v[16:19], v[180:183], v[204:207], v[16:19]
	v_mfma_f32_16x16x32_bf16 v[8:11], v[166:169], v[232:235], v[8:11]
	v_mfma_f32_16x16x32_bf16 v[0:3], v[180:183], v[232:235], v[0:3]
	s_setprio 0
	s_barrier
	s_add_i32 s0, 0, 0x18000
	v_add_u32_e32 v80, s0, v225
	s_add_i32 s33, 0, 0x1c000
	ds_read_b128 v[130:133], v80
	ds_read_b128 v[134:137], v80 offset:1024
	ds_read_b128 v[154:157], v80 offset:2048
	ds_read_b128 v[158:161], v80 offset:3072
	v_add_u32_e32 v80, s33, v225
	ds_read_b128 v[162:165], v80
	ds_read_b128 v[166:169], v80 offset:1024
	ds_read_b128 v[170:173], v80 offset:2048
	ds_read_b128 v[180:183], v80 offset:3072
	s_add_u32 s2, s38, s22
	s_addc_u32 s3, s39, 0
	s_mov_b32 m0, s86
	v_lshl_add_u64 v[244:245], s[2:3], 0, v[138:139]
	ds_read_b128 v[184:187], v227 offset:32768
	ds_read_b128 v[188:191], v227 offset:33792
	ds_read_b128 v[192:195], v227 offset:34816
	ds_read_b128 v[196:199], v227 offset:35840
	ds_read_b128 v[200:203], v227 offset:36864
	ds_read_b128 v[204:207], v227 offset:37888
	ds_read_b128 v[228:231], v227 offset:38912
	ds_read_b128 v[232:235], v227 offset:39936
	global_load_lds_dwordx4 v[244:245], off
	v_lshl_add_u64 v[244:245], s[2:3], 0, v[142:143]
	s_mov_b32 m0, s87
	s_nop 0
	global_load_lds_dwordx4 v[244:245], off
	s_waitcnt vmcnt(8)
	s_waitcnt lgkmcnt(0)
	s_barrier
	s_setprio 1
	v_mfma_f32_16x16x32_bf16 v[126:129], v[130:133], v[184:187], v[126:129]
	v_mfma_f32_16x16x32_bf16 v[118:121], v[154:157], v[184:187], v[118:121]
	v_mfma_f32_16x16x32_bf16 v[110:113], v[130:133], v[192:195], v[110:113]
	v_mfma_f32_16x16x32_bf16 v[102:105], v[154:157], v[192:195], v[102:105]
	v_mfma_f32_16x16x32_bf16 v[94:97], v[130:133], v[200:203], v[94:97]
	v_mfma_f32_16x16x32_bf16 v[86:89], v[154:157], v[200:203], v[86:89]
	v_mfma_f32_16x16x32_bf16 v[76:79], v[130:133], v[228:231], v[76:79]
	v_mfma_f32_16x16x32_bf16 v[68:71], v[154:157], v[228:231], v[68:71]
	v_mfma_f32_16x16x32_bf16 v[126:129], v[134:137], v[188:191], v[126:129]
	v_mfma_f32_16x16x32_bf16 v[118:121], v[158:161], v[188:191], v[118:121]
	v_mfma_f32_16x16x32_bf16 v[110:113], v[134:137], v[196:199], v[110:113]
	v_mfma_f32_16x16x32_bf16 v[102:105], v[158:161], v[196:199], v[102:105]
	v_mfma_f32_16x16x32_bf16 v[94:97], v[134:137], v[204:207], v[94:97]
	v_mfma_f32_16x16x32_bf16 v[86:89], v[158:161], v[204:207], v[86:89]
	v_mfma_f32_16x16x32_bf16 v[76:79], v[134:137], v[232:235], v[76:79]
	v_mfma_f32_16x16x32_bf16 v[68:71], v[158:161], v[232:235], v[68:71]
	v_mfma_f32_16x16x32_bf16 v[122:125], v[162:165], v[184:187], v[122:125]
	v_mfma_f32_16x16x32_bf16 v[114:117], v[170:173], v[184:187], v[114:117]
	v_mfma_f32_16x16x32_bf16 v[106:109], v[162:165], v[192:195], v[106:109]
	v_mfma_f32_16x16x32_bf16 v[98:101], v[170:173], v[192:195], v[98:101]
	v_mfma_f32_16x16x32_bf16 v[90:93], v[162:165], v[200:203], v[90:93]
	v_mfma_f32_16x16x32_bf16 v[82:85], v[170:173], v[200:203], v[82:85]
	v_mfma_f32_16x16x32_bf16 v[72:75], v[162:165], v[228:231], v[72:75]
	v_mfma_f32_16x16x32_bf16 v[64:67], v[170:173], v[228:231], v[64:67]
	s_setprio 0
	s_setprio 1
	v_mfma_f32_16x16x32_bf16 v[122:125], v[166:169], v[188:191], v[122:125]
	v_mfma_f32_16x16x32_bf16 v[114:117], v[180:183], v[188:191], v[114:117]
	v_mfma_f32_16x16x32_bf16 v[106:109], v[166:169], v[196:199], v[106:109]
	v_mfma_f32_16x16x32_bf16 v[98:101], v[180:183], v[196:199], v[98:101]
	v_mfma_f32_16x16x32_bf16 v[90:93], v[166:169], v[204:207], v[90:93]
	v_mfma_f32_16x16x32_bf16 v[82:85], v[180:183], v[204:207], v[82:85]
	v_mfma_f32_16x16x32_bf16 v[72:75], v[166:169], v[232:235], v[72:75]
	v_mfma_f32_16x16x32_bf16 v[64:67], v[180:183], v[232:235], v[64:67]
	s_setprio 0
	s_barrier
; #define PG8_STAGE(bufoff, gbase, voff) do { _Pragma("unroll") for (int _i = 0; _i < 2; ++_i) \
;         __builtin_amdgcn_global_load_lds((const unsigned*)((const char*)(gbase) + (voff)[_i]), (PG8_LAS unsigned*)(lds + (bufoff) + ldsw + _i * 8192), 16, 0, 0); } while (0)
; #define PG8_LDA(dst, b, h) do { _Pragma("unroll") for (int m = 0; m < 4; ++m) _Pragma("unroll") for (int k = 0; k < 2; ++k) dst[m][k] = *(const PG8_LAS bf16x8*)(lds + PG8_SA(b, h) + aoff + m * 2048 + k * 1024); } while (0)
; #define PG8_MMA(ai, bj, At, Bt) do { __builtin_amdgcn_s_setprio(1); _Pragma("unroll") for (int m = 0; m < 4; ++m) _Pragma("unroll") for (int n = 0; n < 2; ++n) _Pragma("unroll") for (int k = 0; k < 2; ++k) \
;         acc[ai][bj][m][n] = __builtin_amdgcn_mfma_f32_16x16x32_bf16(Bt[n][k], At[m][k], acc[ai][bj][m][n], 0, 0, 0); __builtin_amdgcn_s_setprio(0); } while (0)
; #define PG8_WAIT_V(n) asm volatile("s_waitcnt vmcnt(" #n ")" ::: "memory")
; #define PG8_WAIT_L(n) asm volatile("s_waitcnt lgkmcnt(" #n ")" ::: "memory")
; #define PG8_BAR __builtin_amdgcn_s_barrier()
; #define PG8_SCHED __builtin_amdgcn_sched_barrier(0)
; template <class Epi, class Sched, bool ALIGN_EPI = false, bool SP2 = false>
; __device__ __forceinline__ void gemm_phase(PG8_LAS unsigned char* lds, const Gemm g, const Sched& S, const Epi& E) {
;     ...
;             PG8_LDA(At, 1, 1); PG8_STAGE(PG8_SB(1, 0), b3, voffB); PG8_STAGE(PG8_SB(1, 1), b3 + hstep, voffB); PG8_STAGE(PG8_SA(1, 0), a3, voffA);
;             PG8_WAIT_V(8); PG8_WAIT_L(0); PG8_BAR; PG8_MMA(1, 0, At, B0); PG8_MMA(1, 1, At, B1); PG8_BAR; PG8_SCHED;
	s_add_i32 s0, s0, s83
	v_lshl_add_u64 v[174:175], v[174:175], 0, s[66:67]
	s_mov_b32 m0, s0
	ds_read_b128 v[184:187], v227 offset:49152
	ds_read_b128 v[188:191], v227 offset:50176
	ds_read_b128 v[192:195], v227 offset:51200
	ds_read_b128 v[196:199], v227 offset:52224
	ds_read_b128 v[200:203], v227 offset:53248
	ds_read_b128 v[204:207], v227 offset:54272
	ds_read_b128 v[228:231], v227 offset:55296
	ds_read_b128 v[232:235], v227 offset:56320
	global_load_lds_dwordx4 v[174:175], off
	v_lshl_add_u64 v[174:175], v[208:209], 0, s[66:67]
	s_add_i32 m0, s0, 0x2000
	s_add_i32 s0, s33, s83
	global_load_lds_dwordx4 v[174:175], off
	v_lshl_add_u64 v[174:175], v[236:237], 0, s[66:67]
	s_mov_b32 m0, s0
	s_nop 0
	global_load_lds_dwordx4 v[174:175], off
	v_lshl_add_u64 v[174:175], v[238:239], 0, s[66:67]
	s_add_i32 m0, s0, 0x2000
	s_nop 0
	global_load_lds_dwordx4 v[174:175], off
	v_lshl_add_u64 v[174:175], v[240:241], 0, s[66:67]
	s_mov_b32 m0, s65
	s_nop 0
	global_load_lds_dwordx4 v[174:175], off
	v_lshl_add_u64 v[174:175], v[242:243], 0, s[66:67]
	s_mov_b32 m0, s53
	s_nop 0
	global_load_lds_dwordx4 v[174:175], off
	s_waitcnt vmcnt(8)
	s_waitcnt lgkmcnt(0)
	s_barrier
	s_setprio 1
	v_mfma_f32_16x16x32_bf16 v[60:63], v[130:133], v[184:187], v[60:63]
	v_mfma_f32_16x16x32_bf16 v[52:55], v[154:157], v[184:187], v[52:55]
	v_mfma_f32_16x16x32_bf16 v[44:47], v[130:133], v[192:195], v[44:47]
	v_mfma_f32_16x16x32_bf16 v[36:39], v[154:157], v[192:195], v[36:39]
	v_mfma_f32_16x16x32_bf16 v[28:31], v[130:133], v[200:203], v[28:31]
	v_mfma_f32_16x16x32_bf16 v[20:23], v[154:157], v[200:203], v[20:23]
	v_mfma_f32_16x16x32_bf16 v[12:15], v[130:133], v[228:231], v[12:15]
	v_mfma_f32_16x16x32_bf16 v[4:7], v[154:157], v[228:231], v[4:7]
	v_mfma_f32_16x16x32_bf16 v[60:63], v[134:137], v[188:191], v[60:63]
	v_mfma_f32_16x16x32_bf16 v[52:55], v[158:161], v[188:191], v[52:55]
	v_mfma_f32_16x16x32_bf16 v[44:47], v[134:137], v[196:199], v[44:47]
	v_mfma_f32_16x16x32_bf16 v[36:39], v[158:161], v[196:199], v[36:39]
	v_mfma_f32_16x16x32_bf16 v[28:31], v[134:137], v[204:207], v[28:31]
	v_mfma_f32_16x16x32_bf16 v[20:23], v[158:161], v[204:207], v[20:23]
	v_mfma_f32_16x16x32_bf16 v[12:15], v[134:137], v[232:235], v[12:15]
	v_mfma_f32_16x16x32_bf16 v[4:7], v[158:161], v[232:235], v[4:7]
	v_mfma_f32_16x16x32_bf16 v[56:59], v[162:165], v[184:187], v[56:59]
	v_mfma_f32_16x16x32_bf16 v[48:51], v[170:173], v[184:187], v[48:51]
	v_mfma_f32_16x16x32_bf16 v[40:43], v[162:165], v[192:195], v[40:43]
	v_mfma_f32_16x16x32_bf16 v[32:35], v[170:173], v[192:195], v[32:35]
	v_mfma_f32_16x16x32_bf16 v[24:27], v[162:165], v[200:203], v[24:27]
	v_mfma_f32_16x16x32_bf16 v[16:19], v[170:173], v[200:203], v[16:19]
	v_mfma_f32_16x16x32_bf16 v[8:11], v[162:165], v[228:231], v[8:11]
	v_mfma_f32_16x16x32_bf16 v[0:3], v[170:173], v[228:231], v[0:3]
	s_setprio 0
	s_setprio 1
	v_mfma_f32_16x16x32_bf16 v[56:59], v[166:169], v[188:191], v[56:59]
	v_mfma_f32_16x16x32_bf16 v[48:51], v[180:183], v[188:191], v[48:51]
	v_mfma_f32_16x16x32_bf16 v[40:43], v[166:169], v[196:199], v[40:43]
	v_mfma_f32_16x16x32_bf16 v[32:35], v[180:183], v[196:199], v[32:35]
	v_mfma_f32_16x16x32_bf16 v[24:27], v[166:169], v[204:207], v[24:27]
	v_mfma_f32_16x16x32_bf16 v[16:19], v[180:183], v[204:207], v[16:19]
	v_mfma_f32_16x16x32_bf16 v[8:11], v[166:169], v[232:235], v[8:11]
	v_mfma_f32_16x16x32_bf16 v[0:3], v[180:183], v[232:235], v[0:3]
	s_setprio 0
	s_barrier
	s_add_u32 vcc_lo, vcc_lo, 0x100
	s_addc_u32 vcc_hi, vcc_hi, 0
	s_add_u32 s10, s10, 0x100
	s_addc_u32 s11, s11, 0
	s_cmp_ge_u32 s1, s97
	s_mov_b32 s0, s1
	s_cbranch_scc0 .LBB0_33
	s_and_b64 vcc, exec, s[28:29]
	s_cbranch_vccnz .LBB0_37
	v_lshl_add_u32 v154, s54, 8, v147
	s_cmp_lt_i32 s77, 1
	s_mov_b64 s[10:11], -1
	s_cbranch_scc0 .LBB0_38
